# final RMSNorm loop and prologue x-conversion loop software-pipelined (next row's loads in flight while the current row is processed)
# baseline (speedup 1.0000x reference)
; __device__ __forceinline__ unsigned pk2(float lo, float hi) { return pg8::cvt_pk_bf16(lo, hi); }
; __device__ __forceinline__ void p0_prologue(const Args& a, LAS unsigned char* lds, int tid, int lane, int wave, int G) {
;     ...
;     for (int m = gw; m < NTOK; m += NGW) {
;         const f32x4* xr = (const f32x4*)(x + (size_t)m * DM) + lane; u32x2* brow = (u32x2*)(xb + (size_t)m * DM) + lane;
;         float s = 0.f;
; #pragma unroll
;         for (int j = 0; j < 4; ++j) { const f32x4 v = xr[64 * j]; u32x2 w; w.x = pk2(v.x, v.y); w.y = pk2(v.z, v.w); brow[64 * j] = w; s += (v.x * v.x + v.y * v.y) + (v.z * v.z + v.w * v.w); }
;         s = wave_sum(s);
;         if (lane < 16) ssq[(size_t)m * 16 + lane] = (lane == 0) ? s : 0.f;
;     }
.LBB0_178:
	s_cmpk_gt_i32 s0, 0x3fff
	v_lshlrev_b32_e32 v6, 2, v2
	v_lshlrev_b32_e32 v8, 4, v2
	v_mbcnt_lo_u32_b32 v22, -1, 0
	s_cbranch_scc1 .LBB0_183
	s_ashr_i32 s1, s0, 31
	s_lshl_b64 s[8:9], s[0:1], 6
	v_mov_b32_e32 v7, 0
	v_lshl_add_u64 v[4:5], s[8:9], 0, v[6:7]
	s_mov_b64 s[8:9], 0x500000
	s_ashr_i32 s91, s90, 31
	s_lshl_b64 s[10:11], s[0:1], 11
	v_lshl_add_u64 v[4:5], v[4:5], 0, s[8:9]
	s_lshl_b64 s[8:9], s[90:91], 6
	v_lshl_or_b32 v10, v2, 3, s10
	v_mov_b32_e32 v11, s11
	s_lshl_b64 s[10:11], s[90:91], 11
	s_lshl_b64 s[22:23], s[0:1], 12
	v_readlane_b32 s40, v250, 11
	v_readlane_b32 s41, v250, 12
	s_add_u32 s22, s40, s22
	v_mov_b32_e32 v9, v7
	s_addc_u32 s23, s41, s23
	v_mbcnt_hi_u32_b32 v3, -1, v22
	v_lshl_add_u64 v[12:13], s[22:23], 0, v[8:9]
	s_mov_b64 s[22:23], 0xc00
	v_and_b32_e32 v7, 64, v3
	v_cmp_gt_u32_e64 s[6:7], 16, v2
	v_cmp_eq_u32_e64 s[4:5], 0, v2
	v_lshl_add_u64 v[12:13], v[12:13], 0, s[22:23]
	s_lshl_b64 s[22:23], s[90:91], 12
	v_add_u32_e32 v7, 64, v7
	v_xor_b32_e32 v9, 1, v3
	v_xor_b32_e32 v14, 2, v3
	v_xor_b32_e32 v15, 4, v3
	v_xor_b32_e32 v16, 8, v3
	v_xor_b32_e32 v17, 16, v3
	v_xor_b32_e32 v18, 32, v3
	v_readlane_b32 s42, v250, 13
	v_readlane_b32 s43, v250, 14
	v_readlane_b32 s44, v250, 15
	v_readlane_b32 s45, v250, 16
	v_readlane_b32 s46, v250, 17
	v_readlane_b32 s47, v250, 18
	v_readlane_b32 s48, v250, 19
	v_readlane_b32 s49, v250, 20
	v_readlane_b32 s50, v250, 21
	v_readlane_b32 s51, v250, 22
	v_readlane_b32 s52, v250, 23
	v_readlane_b32 s53, v250, 24
	v_readlane_b32 s54, v250, 25
	v_readlane_b32 s55, v250, 26
	global_load_dwordx4 v[24:27], v[12:13], off offset:-3072
	global_load_dwordx4 v[28:31], v[12:13], off offset:-2048
	global_load_dwordx4 v[32:35], v[12:13], off offset:-1024
	global_load_dwordx4 v[36:39], v[12:13], off
	s_waitcnt vmcnt(0)
	s_branch .LBB0_181
.LBB0_180:
	s_or_b64 exec, exec, s[24:25]
	s_waitcnt vmcnt(4)
	v_mov_b32_e32 v24, v48
	v_mov_b32_e32 v25, v49
	v_mov_b32_e32 v26, v50
	v_mov_b32_e32 v27, v51
	v_mov_b32_e32 v28, v52
	v_mov_b32_e32 v29, v53
	v_mov_b32_e32 v30, v54
	v_mov_b32_e32 v31, v55
	v_mov_b32_e32 v32, v56
	v_mov_b32_e32 v33, v57
	v_mov_b32_e32 v34, v58
	v_mov_b32_e32 v35, v59
	v_mov_b32_e32 v36, v60
	v_mov_b32_e32 v37, v61
	v_mov_b32_e32 v38, v62
	v_mov_b32_e32 v39, v63
	s_add_i32 s0, s0, s90
	v_lshl_add_u64 v[4:5], v[4:5], 0, s[8:9]
	v_lshl_add_u64 v[10:11], v[10:11], 0, s[10:11]
	s_cmpk_gt_i32 s0, 0x3fff
	v_lshl_add_u64 v[12:13], v[12:13], 0, s[22:23]
	s_cbranch_scc1 .LBB0_183
.LBB0_181:
	s_add_i32 vcc_lo, s0, s90
	s_cmpk_gt_i32 vcc_lo, 0x3fff
	s_cbranch_scc1 .Lx_nopf
	v_lshl_add_u64 v[44:45], v[12:13], 0, s[22:23]
	global_load_dwordx4 v[48:51], v[44:45], off offset:-3072
	global_load_dwordx4 v[52:55], v[44:45], off offset:-2048
	global_load_dwordx4 v[56:59], v[44:45], off offset:-1024
	global_load_dwordx4 v[60:63], v[44:45], off
.Lx_nopf:
	v_readlane_b32 s12, v250, 0
	v_readlane_b32 s16, v250, 4
	v_readlane_b32 s17, v250, 5
	v_readlane_b32 s13, v250, 1
	s_waitcnt lgkmcnt(0)
	v_lshl_add_u64 v[20:21], s[16:17], 0, v[10:11]
	v_add_co_u32_e32 v40, vcc, 0xb600000, v20
	v_cvt_pk_bf16_f32 v20, v24, v25
	v_readlane_b32 s14, v250, 2
	v_addc_co_u32_e32 v41, vcc, 0, v21, vcc
	v_cvt_pk_bf16_f32 v21, v26, v27
	global_store_dwordx2 v[40:41], v[20:21], off
	v_cvt_pk_bf16_f32 v20, v28, v29
	v_cvt_pk_bf16_f32 v21, v30, v31
	global_store_dwordx2 v[40:41], v[20:21], off offset:512
	v_cvt_pk_bf16_f32 v20, v32, v33
	v_cvt_pk_bf16_f32 v21, v34, v35
	global_store_dwordx2 v[40:41], v[20:21], off offset:1024
	v_cmp_lt_i32_e32 vcc, v9, v7
	v_readlane_b32 s15, v250, 3
	v_readlane_b32 s18, v250, 6
	v_cndmask_b32_e32 v19, v3, v9, vcc
	v_lshlrev_b32_e32 v19, 2, v19
	v_cmp_lt_i32_e32 vcc, v14, v7
	v_readlane_b32 s19, v250, 7
	v_mul_f32_e32 v20, v25, v25
	v_mul_f32_e32 v21, v27, v27
	v_fmac_f32_e32 v20, v24, v24
	v_fmac_f32_e32 v21, v26, v26
	v_add_f32_e32 v20, v20, v21
	v_cvt_pk_bf16_f32 v24, v36, v37
	v_cvt_pk_bf16_f32 v25, v38, v39
	global_store_dwordx2 v[40:41], v[24:25], off offset:1536
	v_mul_f32_e32 v21, v29, v29
	v_mul_f32_e32 v23, v31, v31
	v_fmac_f32_e32 v21, v28, v28
	v_fmac_f32_e32 v23, v30, v30
	v_add_f32_e32 v21, v21, v23
	v_add_f32_e32 v20, v20, v21
	v_mul_f32_e32 v21, v33, v33
	v_mul_f32_e32 v23, v35, v35
	v_fmac_f32_e32 v21, v32, v32
	v_fmac_f32_e32 v23, v34, v34
	v_add_f32_e32 v21, v21, v23
	v_add_f32_e32 v20, v20, v21
	v_mul_f32_e32 v21, v37, v37
	v_mul_f32_e32 v23, v39, v39
	v_fmac_f32_e32 v21, v36, v36
	v_fmac_f32_e32 v23, v38, v38
	v_add_f32_e32 v21, v21, v23
	v_add_f32_e32 v20, v20, v21
	ds_bpermute_b32 v19, v19, v20
	v_cndmask_b32_e32 v21, v3, v14, vcc
	v_lshlrev_b32_e32 v21, 2, v21
	v_cmp_lt_i32_e32 vcc, v15, v7
	s_waitcnt lgkmcnt(0)
	v_add_f32_e32 v19, v20, v19
	ds_bpermute_b32 v20, v21, v19
	v_cndmask_b32_e32 v21, v3, v15, vcc
	v_lshlrev_b32_e32 v21, 2, v21
	v_cmp_lt_i32_e32 vcc, v16, v7
	s_waitcnt lgkmcnt(0)
	v_add_f32_e32 v19, v19, v20
	ds_bpermute_b32 v20, v21, v19
	v_cndmask_b32_e32 v21, v3, v16, vcc
	v_lshlrev_b32_e32 v21, 2, v21
	v_cmp_lt_i32_e32 vcc, v17, v7
	s_waitcnt lgkmcnt(0)
	v_add_f32_e32 v19, v19, v20
	ds_bpermute_b32 v20, v21, v19
	v_cndmask_b32_e32 v21, v3, v17, vcc
	v_lshlrev_b32_e32 v21, 2, v21
	v_cmp_lt_i32_e32 vcc, v18, v7
	s_waitcnt lgkmcnt(0)
	v_add_f32_e32 v19, v19, v20
	ds_bpermute_b32 v20, v21, v19
	v_cndmask_b32_e32 v21, v3, v18, vcc
	s_waitcnt lgkmcnt(0)
	v_add_f32_e32 v19, v19, v20
	v_lshlrev_b32_e32 v20, 2, v21
	ds_bpermute_b32 v20, v20, v19
	s_and_saveexec_b64 s[24:25], s[6:7]
	s_cbranch_execz .LBB0_180
	v_readlane_b32 s12, v250, 0
	s_waitcnt lgkmcnt(0)
	v_add_f32_e32 v19, v19, v20
	v_readlane_b32 s16, v250, 4
	v_readlane_b32 s17, v250, 5
	v_cndmask_b32_e64 v19, 0, v19, s[4:5]
	v_readlane_b32 s13, v250, 1
	v_lshl_add_u64 v[20:21], s[16:17], 0, v[4:5]
	v_readlane_b32 s14, v250, 2
	v_readlane_b32 s15, v250, 3
	v_readlane_b32 s18, v250, 6
	v_readlane_b32 s19, v250, 7
	global_store_dword v[20:21], v19, off
	s_branch .LBB0_180

; __global__ void __launch_bounds__(NTHR, 2) fwd_kernel(Args a) {
;     ...
;     { PH_IDS
;         const int gw = blockIdx.x * NWAVE + wave, NGW = G * NWAVE; const float* fn = a.in[32];
;         for (int m = gw; m < NTOK; m += NGW) {
;             const u32x2* xr = (const u32x2*)(XB + (size_t)m * DM) + lane; f32x4* orow = (f32x4*)(a.out + (size_t)m * DM) + lane; f32x4 v[4]; float s = 0.f;
; #pragma unroll
;             for (int j = 0; j < 4; ++j) { const u32x2 r = xr[64 * j]; v[j] = (f32x4){__uint_as_float(r.x << 16), __uint_as_float(r.x & 0xffff0000u), __uint_as_float(r.y << 16), __uint_as_float(r.y & 0xffff0000u)};
;                 s += (v[j].x * v[j].x + v[j].y * v[j].y) + (v[j].z * v[j].z + v[j].w * v[j].w); }
;             const float rstd = rsqrtf(wave_sum(s) * (1.0f / DM) + EPS);
; #pragma unroll
;             for (int j = 0; j < 4; ++j) { const f32x4 gn = *((const f32x4*)fn + lane + 64 * j); orow[64 * j] = v[j] * rstd * gn; }
;         }
.LBB0_1974:
	v_readlane_b32 s1, v251, 13
	v_readfirstlane_b32 s0, v174
	s_ashr_i32 s0, s0, 6
	s_add_i32 s0, s0, s1
	s_cmpk_gt_i32 s0, 0x3fff
	v_readlane_b32 s6, v251, 25
	v_readlane_b32 s7, v251, 26
	s_cbranch_scc1 .LBB0_1977
	v_and_b32_e32 v0, 64, v175
	v_add_u32_e32 v0, 64, v0
	v_xor_b32_e32 v1, 1, v175
	v_cmp_lt_i32_e32 vcc, v1, v0
	v_readlane_b32 s8, v250, 0
	s_ashr_i32 s1, s0, 31
	v_cndmask_b32_e32 v1, v175, v1, vcc
	v_lshlrev_b32_e32 v6, 2, v1
	v_xor_b32_e32 v1, 2, v175
	v_cmp_lt_i32_e32 vcc, v1, v0
	v_readlane_b32 s12, v250, 4
	s_lshl_b64 s[2:3], s[0:1], 11
	v_cndmask_b32_e32 v1, v175, v1, vcc
	v_lshlrev_b32_e32 v7, 2, v1
	v_xor_b32_e32 v1, 4, v175
	v_cmp_lt_i32_e32 vcc, v1, v0
	v_and_b32_e32 v2, 63, v174
	v_mov_b32_e32 v5, 0
	v_cndmask_b32_e32 v1, v175, v1, vcc
	v_lshlrev_b32_e32 v8, 2, v1
	v_xor_b32_e32 v1, 8, v175
	v_cmp_lt_i32_e32 vcc, v1, v0
	v_readlane_b32 s13, v250, 5
	s_add_u32 s2, s12, s2
	v_cndmask_b32_e32 v1, v175, v1, vcc
	v_lshlrev_b32_e32 v9, 2, v1
	v_xor_b32_e32 v1, 16, v175
	v_cmp_lt_i32_e32 vcc, v1, v0
	v_lshlrev_b32_e32 v4, 4, v2
	v_lshlrev_b32_e32 v2, 3, v2
	v_mov_b32_e32 v3, v5
	s_addc_u32 s3, s13, s3
	v_cndmask_b32_e32 v1, v175, v1, vcc
	v_lshl_add_u64 v[2:3], s[2:3], 0, v[2:3]
	s_mov_b64 s[2:3], 0xb600000
	s_ashr_i32 s7, s6, 31
	v_lshlrev_b32_e32 v10, 2, v1
	v_xor_b32_e32 v1, 32, v175
	v_readlane_b32 s10, v250, 2
	v_lshl_add_u64 v[2:3], v[2:3], 0, s[2:3]
	s_lshl_b64 s[2:3], s[6:7], 11
	s_lshl_b64 s[4:5], s[0:1], 12
	v_cmp_lt_i32_e32 vcc, v1, v0
	v_readlane_b32 s11, v250, 3
	s_add_u32 s4, s10, s4
	v_cndmask_b32_e32 v0, v175, v1, vcc
	v_readlane_b32 s9, v250, 1
	s_addc_u32 s5, s11, s5
	v_lshlrev_b32_e32 v11, 2, v0
	v_lshl_add_u64 v[0:1], s[8:9], 0, v[4:5]
	v_lshl_add_u64 v[4:5], s[4:5], 0, v[4:5]
	s_mov_b64 s[4:5], 0xc00
	v_lshl_add_u64 v[4:5], v[4:5], 0, s[4:5]
	s_lshl_b64 s[4:5], s[6:7], 12
	v_mov_b32_e32 v12, 0x358637bd
	s_mov_b32 s1, 0x800000
	v_readlane_b32 s14, v250, 6
	v_readlane_b32 s15, v250, 7
	global_load_dwordx4 v[100:103], v[0:1], off
	global_load_dwordx4 v[104:107], v[0:1], off offset:1024
	global_load_dwordx4 v[108:111], v[0:1], off offset:2048
	global_load_dwordx4 v[112:115], v[0:1], off offset:3072
	global_load_dwordx2 v[18:19], v[2:3], off
	global_load_dwordx2 v[20:21], v[2:3], off offset:512
	global_load_dwordx2 v[22:23], v[2:3], off offset:1024
	global_load_dwordx2 v[24:25], v[2:3], off offset:1536
	s_waitcnt vmcnt(0)
.LBB0_1976:
	s_add_i32 s0, s0, s6
	v_lshl_add_u64 v[2:3], v[2:3], 0, s[2:3]
	s_cmpk_gt_i32 s0, 0x3fff
	global_load_dwordx2 v[120:121], v[2:3], off
	global_load_dwordx2 v[122:123], v[2:3], off offset:512
	global_load_dwordx2 v[124:125], v[2:3], off offset:1024
	global_load_dwordx2 v[126:127], v[2:3], off offset:1536
	v_lshlrev_b32_e32 v26, 16, v18
	v_and_b32_e32 v27, 0xffff0000, v18
	v_lshlrev_b32_e32 v18, 16, v19
	v_and_b32_e32 v19, 0xffff0000, v19
	v_lshlrev_b32_e32 v29, 16, v21
	v_lshlrev_b32_e32 v28, 16, v20
	v_and_b32_e32 v21, 0xffff0000, v21
	v_and_b32_e32 v20, 0xffff0000, v20
	v_and_b32_e32 v31, 0xffff0000, v22
	v_lshlrev_b32_e32 v33, 16, v24
	v_and_b32_e32 v35, 0xffff0000, v24
	v_mul_f32_e32 v32, v19, v19
	v_mul_f32_e32 v34, v27, v27
	v_lshlrev_b32_e32 v30, 16, v22
	v_lshlrev_b32_e32 v22, 16, v23
	v_and_b32_e32 v23, 0xffff0000, v23
	v_pk_mul_f32 v[36:37], v[20:21], v[20:21]
	v_mov_b32_e32 v39, v33
	v_mul_f32_e32 v38, v31, v31
	v_pk_fma_f32 v[42:43], v[18:19], v[18:19], v[32:33] op_sel_hi:[1,1,0]
	v_pk_fma_f32 v[44:45], v[26:27], v[26:27], v[34:35] op_sel_hi:[1,1,0]
	v_lshlrev_b32_e32 v24, 16, v25
	v_and_b32_e32 v25, 0xffff0000, v25
	v_mul_f32_e32 v40, v23, v23
	v_pk_fma_f32 v[36:37], v[28:29], v[28:29], v[36:37]
	v_pk_fma_f32 v[46:47], v[30:31], v[30:31], v[38:39] op_sel_hi:[1,1,0]
	v_mov_b32_e32 v32, v44
	v_mov_b32_e32 v38, v42
	v_mul_f32_e32 v13, v35, v35
	v_mul_f32_e32 v48, v24, v24
	v_mul_f32_e32 v49, v25, v25
	v_pk_fma_f32 v[40:41], v[22:23], v[22:23], v[40:41] op_sel_hi:[1,1,0]
	v_pk_add_f32 v[42:43], v[44:45], v[42:43]
	v_pk_add_f32 v[36:37], v[36:37], v[36:37] op_sel:[0,1] op_sel_hi:[1,0]
	v_pk_mul_f32 v[38:39], v[32:33], v[38:39]
	v_mov_b32_e32 v47, v48
	v_mov_b32_e32 v41, v49
	v_mov_b32_e32 v37, v13
	v_mov_b32_e32 v43, v39
	v_pk_add_f32 v[40:41], v[46:47], v[40:41]
	v_pk_add_f32 v[36:37], v[42:43], v[36:37]
	v_mov_b32_e32 v34, v33
	v_pk_add_f32 v[36:37], v[36:37], v[40:41]
	s_nop 0
	v_add_f32_e32 v13, v36, v37
	ds_bpermute_b32 v32, v6, v13
	s_waitcnt lgkmcnt(0)
	v_add_f32_e32 v13, v13, v32
	ds_bpermute_b32 v32, v7, v13
	s_waitcnt lgkmcnt(0)
	v_add_f32_e32 v13, v13, v32
	ds_bpermute_b32 v32, v8, v13
	s_waitcnt lgkmcnt(0)
	v_add_f32_e32 v13, v13, v32
	ds_bpermute_b32 v32, v9, v13
	s_waitcnt lgkmcnt(0)
	v_add_f32_e32 v13, v13, v32
	ds_bpermute_b32 v32, v10, v13
	s_waitcnt lgkmcnt(0)
	v_add_f32_e32 v13, v13, v32
	ds_bpermute_b32 v32, v11, v13
	s_waitcnt lgkmcnt(0)
	v_add_f32_e32 v13, v13, v32
	v_fmamk_f32 v13, v13, 0x3a800000, v12
	v_mul_f32_e32 v32, 0x4b800000, v13
	v_cmp_gt_f32_e32 vcc, s1, v13
	s_nop 1
	v_cndmask_b32_e32 v13, v13, v32, vcc
	v_rsq_f32_e32 v13, v13
	s_nop 0
	v_mul_f32_e32 v32, 0x45800000, v13
	v_cndmask_b32_e32 v32, v13, v32, vcc
	v_pk_mul_f32 v[26:27], v[32:33], v[26:27] op_sel_hi:[0,1]
	v_pk_mul_f32 v[18:19], v[32:33], v[18:19] op_sel_hi:[0,1]
	v_pk_mul_f32 v[16:17], v[102:103], v[18:19]
	v_pk_mul_f32 v[14:15], v[100:101], v[26:27]
	global_store_dwordx4 v[4:5], v[14:17], off offset:-3072
	v_mov_b32_e32 v18, v29
	v_mov_b32_e32 v19, v21
	v_mov_b32_e32 v29, v20
	v_pk_mul_f32 v[18:19], v[32:33], v[18:19] op_sel_hi:[0,1]
	v_pk_mul_f32 v[20:21], v[32:33], v[28:29] op_sel_hi:[0,1]
	v_pk_mul_f32 v[128:129], v[104:105], v[20:21]
	v_pk_mul_f32 v[130:131], v[106:107], v[18:19]
	global_store_dwordx4 v[4:5], v[128:131], off offset:-2048
	v_pk_mul_f32 v[18:19], v[32:33], v[22:23] op_sel_hi:[0,1]
	v_pk_mul_f32 v[20:21], v[32:33], v[30:31] op_sel_hi:[0,1]
	v_pk_mul_f32 v[132:133], v[108:109], v[20:21]
	v_pk_mul_f32 v[134:135], v[110:111], v[18:19]
	global_store_dwordx4 v[4:5], v[132:135], off offset:-1024
	v_pk_mul_f32 v[18:19], v[32:33], v[24:25] op_sel_hi:[0,1]
	v_pk_mul_f32 v[20:21], v[32:33], v[34:35] op_sel_hi:[0,1]
	v_pk_mul_f32 v[136:137], v[112:113], v[20:21]
	v_pk_mul_f32 v[138:139], v[114:115], v[18:19]
	global_store_dwordx4 v[4:5], v[136:139], off
	v_lshl_add_u64 v[4:5], v[4:5], 0, s[4:5]
	s_waitcnt vmcnt(4)
	v_mov_b32_e32 v18, v120
	v_mov_b32_e32 v19, v121
	v_mov_b32_e32 v20, v122
	v_mov_b32_e32 v21, v123
	v_mov_b32_e32 v22, v124
	v_mov_b32_e32 v23, v125
	v_mov_b32_e32 v24, v126
	v_mov_b32_e32 v25, v127
	s_cbranch_scc0 .LBB0_1976
